# MLA tile loop: cross-half row max via v_permlane32_swap instead of ds_bpermute (on top of v22: two-level publishes, static tickets, top-level poll)
# speedup vs baseline: 1.0097x; 1.0044x over previous
; #define LAS __attribute__((address_space(3)))
; DI float ex2(float x) { return __builtin_amdgcn_exp2f(x); }
; DI float shx(float v, int lane, int m) { return __builtin_bit_cast(float, __builtin_amdgcn_ds_bpermute((lane ^ m) << 2, __builtin_bit_cast(int, v))); }
; DI void mla_item(int g_wave, LAS unsigned char* lds, const bf16_t* QN, const bf16_t* QR, const bf16_t* KN, const bf16_t* KRb, const bf16_t* VM, bf16_t* MIX,
;                  int kvbase, int qrow0, int nq, int head, int ntiles, int wt) {
;     ...
;     for (int T = 0; T < ntiles; ++T) {
;         if (T + 1 < ntiles) MLA_LOAD(T + 1);
;         if (T < wt) {
;             LAS const unsigned char* base = lds + (T & 1) * BUF;
;             f32x16 s0, s1;
; #pragma unroll
;             for (int i = 0; i < 16; ++i) { s0[i] = 0.f; s1[i] = 0.f; }
; #pragma unroll
;             for (int s = 0; s < 6; ++s) {
;                 const bf16x8 a0 = *(LAS const bf16x8*)(base + r * KST + (16 * s + 8 * h) * 2);
;                 const bf16x8 a1 = *(LAS const bf16x8*)(base + (32 + r) * KST + (16 * s + 8 * h) * 2);
;                 s0 = MFMA32(a0, qf[s], s0); s1 = MFMA32(a1, qf[s], s1);
;             }
;             float mx = s0[0];
; #pragma unroll
;             for (int i = 0; i < 16; ++i) { mx = fmaxf(mx, s0[i]); mx = fmaxf(mx, s1[i]); }
;             mx = fmaxf(mx, shx(mx, lane, 32));
;             const float m_new = fmaxf(m_run, mx), alpha = ex2(m_run - m_new);
;             m_run = m_new;
;             float ls = 0.f;
; #pragma unroll
;             for (int i = 0; i < 16; ++i) { s0[i] = ex2(s0[i] - m_new); s1[i] = ex2(s1[i] - m_new); ls += s0[i] + s1[i]; }
;             l_run = l_run * alpha + ls;
; #pragma unroll
;             for (int i = 0; i < 16; ++i) { o0[i] *= alpha; o1[i] *= alpha; }
;             LAS const unsigned char* vb = base + KB;
; #pragma unroll
;             for (int kt = 0; kt < 2; ++kt)
; #pragma unroll
;                 for (int ss = 0; ss < 2; ++ss) {
;                     const bf16x8 pb = packfrag(kt == 0 ? s0 : s1, ss);
;                     LAS const unsigned char* vp = vb + (32 * kt + 16 * ss + 4 * h + tq) * VST + (16 * blk + 4 * tp) * 2;
;                     const bf16x8 a0 = tr_frag(vp, 8 * VST), a1 = tr_frag(vp + 64, 8 * VST);
;                     o0 = MFMA32(a0, pb, o0); o1 = MFMA32(a1, pb, o1);
;                 }
;         }
.LBB0_1012:
	s_or_b64 exec, exec, s[4:5]
	v_cmp_lt_i32_e32 vcc, s7, v118
	s_and_saveexec_b64 s[4:5], vcc
	s_cbranch_execz .LBB0_1014
	s_bitcmp1_b32 s7, 0
	s_cselect_b32 s8, 0x5800, 0
	s_add_i32 s8, s8, 0
	v_add3_u32 v109, s8, v122, v100
	ds_read_b128 v[32:35], v109 offset:6656
	ds_read_b128 v[36:39], v109
	ds_read_b128 v[110:113], v109 offset:32
	ds_read_b128 v[124:127], v109 offset:6688
	s_waitcnt lgkmcnt(2)
	v_mfma_f32_32x32x16_bf16 v[48:63], v[36:39], v[84:87], 0
	v_mfma_f32_32x32x16_bf16 v[32:47], v[32:35], v[84:87], 0
	s_waitcnt lgkmcnt(1)
	v_mfma_f32_32x32x16_bf16 v[48:63], v[110:113], v[80:83], v[48:63]
	s_waitcnt lgkmcnt(0)
	v_mfma_f32_32x32x16_bf16 v[32:47], v[124:127], v[80:83], v[32:47]
	ds_read_b128 v[110:113], v109 offset:64
	ds_read_b128 v[124:127], v109 offset:6720
	s_waitcnt lgkmcnt(1)
	v_mfma_f32_32x32x16_bf16 v[48:63], v[110:113], v[76:79], v[48:63]
	s_waitcnt lgkmcnt(0)
	v_mfma_f32_32x32x16_bf16 v[32:47], v[124:127], v[76:79], v[32:47]
	ds_read_b128 v[110:113], v109 offset:96
	ds_read_b128 v[124:127], v109 offset:6752
	s_waitcnt lgkmcnt(1)
	v_mfma_f32_32x32x16_bf16 v[48:63], v[110:113], v[68:71], v[48:63]
	s_waitcnt lgkmcnt(0)
	v_mfma_f32_32x32x16_bf16 v[32:47], v[124:127], v[68:71], v[32:47]
	ds_read_b128 v[110:113], v109 offset:128
	ds_read_b128 v[124:127], v109 offset:6784
	s_waitcnt lgkmcnt(1)
	v_mfma_f32_32x32x16_bf16 v[48:63], v[110:113], v[72:75], v[48:63]
	s_waitcnt lgkmcnt(0)
	v_mfma_f32_32x32x16_bf16 v[32:47], v[124:127], v[72:75], v[32:47]
	ds_read_b128 v[110:113], v109 offset:160
	ds_read_b128 v[124:127], v109 offset:6816
	s_waitcnt lgkmcnt(1)
	v_mfma_f32_32x32x16_bf16 v[48:63], v[110:113], v[64:67], v[48:63]
	s_waitcnt lgkmcnt(0)
	v_mfma_f32_32x32x16_bf16 v[32:47], v[124:127], v[64:67], v[32:47]
	s_nop 9
	v_max_f32_e32 v110, v48, v48
	s_nop 0
	v_max_f32_e32 v109, v32, v32
	v_max_f32_e32 v109, v110, v109
	v_max3_f32 v109, v109, v49, v33
	v_max3_f32 v109, v109, v50, v34
	v_max3_f32 v109, v109, v51, v35
	v_max3_f32 v109, v109, v52, v36
	v_max3_f32 v109, v109, v53, v37
	v_max3_f32 v109, v109, v54, v38
	v_max3_f32 v109, v109, v55, v39
	v_max3_f32 v109, v109, v56, v40
	v_max3_f32 v109, v109, v57, v41
	v_max3_f32 v109, v109, v58, v42
	v_max3_f32 v109, v109, v59, v43
	v_max3_f32 v109, v109, v60, v44
	v_max3_f32 v109, v109, v61, v45
	v_max3_f32 v109, v109, v62, v46
	v_max3_f32 v109, v109, v63, v47
	v_mov_b32_e32 v110, v109
	s_nop 1
	v_permlane32_swap_b32_e32 v109, v110
	v_max3_f32 v124, v108, v109, v110
	v_sub_f32_e32 v32, v32, v124
	v_exp_f32_e32 v125, v32
	v_sub_f32_e32 v32, v49, v124
	v_sub_f32_e32 v132, v108, v124
	v_exp_f32_e32 v108, v32
	v_sub_f32_e32 v32, v33, v124
	v_sub_f32_e32 v33, v50, v124
	v_exp_f32_e32 v134, v33
	v_sub_f32_e32 v33, v34, v124
	v_exp_f32_e32 v126, v33
	v_sub_f32_e32 v33, v51, v124
	v_sub_f32_e32 v48, v48, v124
	v_exp_f32_e32 v110, v33
	v_sub_f32_e32 v33, v35, v124
	v_exp_f32_e32 v133, v48
	v_exp_f32_e32 v48, v33
	v_sub_f32_e32 v33, v52, v124
	v_exp_f32_e32 v135, v33
	v_sub_f32_e32 v33, v36, v124
	v_exp_f32_e32 v127, v33
	v_sub_f32_e32 v33, v53, v124
	v_exp_f32_e32 v112, v33
	v_sub_f32_e32 v33, v37, v124
	v_exp_f32_e32 v50, v33
	v_sub_f32_e32 v33, v54, v124
	v_exp_f32_e32 v136, v33
	v_sub_f32_e32 v33, v38, v124
	v_exp_f32_e32 v129, v33
	v_sub_f32_e32 v33, v55, v124
	v_exp_f32_e32 v130, v33
	v_sub_f32_e32 v33, v39, v124
	v_exp_f32_e32 v52, v33
	v_sub_f32_e32 v33, v56, v124
	v_exp_f32_e32 v138, v33
	v_sub_f32_e32 v33, v40, v124
	v_exp_f32_e32 v35, v33
	v_sub_f32_e32 v33, v57, v124
	v_exp_f32_e32 v54, v33
	v_sub_f32_e32 v33, v41, v124
	v_exp_f32_e32 v36, v33
	v_sub_f32_e32 v33, v58, v124
	v_exp_f32_e32 v139, v33
	v_sub_f32_e32 v33, v42, v124
	v_exp_f32_e32 v128, v33
	v_sub_f32_e32 v33, v59, v124
	v_exp_f32_e32 v56, v33
	v_sub_f32_e32 v33, v43, v124
	v_exp_f32_e32 v38, v33
	v_sub_f32_e32 v33, v60, v124
	v_exp_f32_e32 v140, v33
	v_sub_f32_e32 v33, v44, v124
	v_exp_f32_e32 v60, v33
	v_sub_f32_e32 v33, v61, v124
	v_exp_f32_e32 v58, v33
	v_sub_f32_e32 v33, v45, v124
	v_exp_f32_e32 v40, v33
	v_sub_f32_e32 v33, v62, v124
	v_exp_f32_e32 v32, v32
	v_exp_f32_e32 v61, v33
	v_sub_f32_e32 v33, v46, v124
	v_exp_f32_e32 v46, v33
	v_sub_f32_e32 v33, v63, v124
	v_exp_f32_e32 v44, v33
	v_sub_f32_e32 v33, v47, v124
	v_add_f32_e32 v109, v133, v125
	v_exp_f32_e32 v42, v33
	v_mov_b32_e32 v33, v225
	v_pk_add_f32 v[62:63], v[108:109], v[32:33]
	v_add_f32_e32 v111, v134, v126
	v_pk_add_f32 v[62:63], v[62:63], v[62:63] op_sel_hi:[0,1]
	v_mov_b32_e32 v49, v63
	v_pk_add_f32 v[62:63], v[110:111], v[48:49]
	v_add_f32_e32 v113, v135, v127
	v_pk_add_f32 v[62:63], v[62:63], v[62:63] op_sel_hi:[0,1]
	v_mov_b32_e32 v51, v63
	v_pk_add_f32 v[62:63], v[112:113], v[50:51]
	v_add_f32_e32 v131, v136, v129
	v_pk_add_f32 v[62:63], v[62:63], v[62:63] op_sel_hi:[0,1]
	v_mov_b32_e32 v53, v63
	v_add3_u32 v47, s8, v116, v117
	v_exp_f32_e32 v34, v132
	v_pk_add_f32 v[62:63], v[130:131], v[52:53]
	v_cvt_pk_bf16_f32 v108, v133, v108
	v_cvt_pk_bf16_f32 v109, v134, v110
	v_cvt_pk_bf16_f32 v110, v135, v112
	v_cvt_pk_bf16_f32 v111, v136, v130
	ds_read_b64_tr_b16 v[130:131], v47 offset:13312
	ds_read_b64_tr_b16 v[132:133], v47 offset:14464
	ds_read_b64_tr_b16 v[134:135], v47 offset:13376
	ds_read_b64_tr_b16 v[136:137], v47 offset:14528
	v_pk_mul_f32 v[14:15], v[14:15], v[34:35] op_sel_hi:[1,0]
	v_pk_mul_f32 v[12:13], v[12:13], v[34:35] op_sel_hi:[1,0]
	v_pk_mul_f32 v[10:11], v[10:11], v[34:35] op_sel_hi:[1,0]
	v_pk_mul_f32 v[8:9], v[8:9], v[34:35] op_sel_hi:[1,0]
	v_pk_mul_f32 v[6:7], v[6:7], v[34:35] op_sel_hi:[1,0]
	v_pk_mul_f32 v[4:5], v[4:5], v[34:35] op_sel_hi:[1,0]
	v_pk_mul_f32 v[2:3], v[2:3], v[34:35] op_sel_hi:[1,0]
	v_pk_mul_f32 v[0:1], v[0:1], v[34:35] op_sel_hi:[1,0]
	v_pk_mul_f32 v[30:31], v[30:31], v[34:35] op_sel_hi:[1,0]
	v_pk_mul_f32 v[28:29], v[28:29], v[34:35] op_sel_hi:[1,0]
	v_pk_mul_f32 v[26:27], v[26:27], v[34:35] op_sel_hi:[1,0]
	v_pk_mul_f32 v[24:25], v[24:25], v[34:35] op_sel_hi:[1,0]
	v_pk_mul_f32 v[22:23], v[22:23], v[34:35] op_sel_hi:[1,0]
	v_pk_mul_f32 v[20:21], v[20:21], v[34:35] op_sel_hi:[1,0]
	v_pk_mul_f32 v[18:19], v[18:19], v[34:35] op_sel_hi:[1,0]
	v_pk_mul_f32 v[16:17], v[16:17], v[34:35] op_sel_hi:[1,0]
	s_waitcnt lgkmcnt(2)
; #define LAS __attribute__((address_space(3)))
; DI float ex2(float x) { return __builtin_amdgcn_exp2f(x); }
; #define MFMA32(a, b, c) __builtin_amdgcn_mfma_f32_32x32x16_bf16((a), (b), (c), 0, 0, 0)
; DI bf16x8 tr_frag(LAS const unsigned char* p, int hi_off) { s16x4 lo = trr(p), hi = trr(p + hi_off); return __builtin_shufflevector(lo, hi, 0, 1, 2, 3, 4, 5, 6, 7); }
; DI void mla_item(int g_wave, LAS unsigned char* lds, const bf16_t* QN, const bf16_t* QR, const bf16_t* KN, const bf16_t* KRb, const bf16_t* VM, bf16_t* MIX,
;                  int kvbase, int qrow0, int nq, int head, int ntiles, int wt) {
;     ...
;             float ls = 0.f;
; #pragma unroll
;             for (int i = 0; i < 16; ++i) { s0[i] = ex2(s0[i] - m_new); s1[i] = ex2(s1[i] - m_new); ls += s0[i] + s1[i]; }
;             l_run = l_run * alpha + ls;
; #pragma unroll
;             for (int i = 0; i < 16; ++i) { o0[i] *= alpha; o1[i] *= alpha; }
;             LAS const unsigned char* vb = base + KB;
; #pragma unroll
;             for (int kt = 0; kt < 2; ++kt)
; #pragma unroll
;                 for (int ss = 0; ss < 2; ++ss) {
;                     const bf16x8 pb = packfrag(kt == 0 ? s0 : s1, ss);
;                     LAS const unsigned char* vp = vb + (32 * kt + 16 * ss + 4 * h + tq) * VST + (16 * blk + 4 * tp) * 2;
;                     const bf16x8 a0 = tr_frag(vp, 8 * VST), a1 = tr_frag(vp + 64, 8 * VST);
;                     o0 = MFMA32(a0, pb, o0); o1 = MFMA32(a1, pb, o1);
;                 }
	v_mfma_f32_32x32x16_bf16 v[0:15], v[130:133], v[108:111], v[0:15]
	v_pk_add_f32 v[62:63], v[62:63], v[62:63] op_sel_hi:[0,1]
	v_add_f32_e32 v55, v138, v35
	v_mov_b32_e32 v37, v63
	v_pk_add_f32 v[62:63], v[54:55], v[36:37]
	v_add_f32_e32 v57, v139, v128
	v_pk_add_f32 v[62:63], v[62:63], v[62:63] op_sel_hi:[0,1]
	v_mov_b32_e32 v39, v63
	s_waitcnt lgkmcnt(0)
	v_mfma_f32_32x32x16_bf16 v[16:31], v[134:137], v[108:111], v[16:31]
	ds_read_b64_tr_b16 v[108:109], v47 offset:15616
	ds_read_b64_tr_b16 v[110:111], v47 offset:16768
	ds_read_b64_tr_b16 v[130:131], v47 offset:15680
	ds_read_b64_tr_b16 v[132:133], v47 offset:16832
	v_add_f32_e64 v62, v56, v38
	v_add_f32_e64 v63, v57, v39
	v_cvt_pk_bf16_f32 v54, v138, v54
	v_cvt_pk_bf16_f32 v55, v139, v56
	v_cvt_pk_bf16_f32 v56, v140, v58
	v_cvt_pk_bf16_f32 v57, v61, v44
	v_pk_add_f32 v[62:63], v[62:63], v[62:63] op_sel_hi:[0,1]
	v_add_f32_e32 v59, v140, v60
	s_waitcnt lgkmcnt(2)
	v_mfma_f32_32x32x16_bf16 v[0:15], v[108:111], v[54:57], v[0:15]
	v_mov_b32_e32 v41, v63
	v_add_f32_e64 v62, v58, v40
	v_add_f32_e64 v63, v59, v41
	v_add_f32_e32 v45, v61, v46
	v_pk_add_f32 v[62:63], v[62:63], v[62:63] op_sel_hi:[0,1]
	v_mov_b32_e32 v43, v63
	v_pk_add_f32 v[62:63], v[44:45], v[42:43]
	v_cvt_pk_bf16_f32 v37, v128, v38
	s_waitcnt lgkmcnt(0)
	v_mfma_f32_32x32x16_bf16 v[16:31], v[130:133], v[54:57], v[16:31]
	v_cvt_pk_bf16_f32 v55, v126, v48
	v_cvt_pk_bf16_f32 v56, v127, v50
	ds_read_b64_tr_b16 v[48:49], v47 offset:17920
	ds_read_b64_tr_b16 v[50:51], v47 offset:19072
	ds_read_b64_tr_b16 v[108:109], v47 offset:17984
	ds_read_b64_tr_b16 v[110:111], v47 offset:19136
	v_cvt_pk_bf16_f32 v54, v125, v32
	v_cvt_pk_bf16_f32 v57, v129, v52
	v_cvt_pk_bf16_f32 v38, v60, v40
	v_cvt_pk_bf16_f32 v39, v46, v42
	s_waitcnt lgkmcnt(2)
	v_mfma_f32_32x32x16_bf16 v[0:15], v[48:51], v[54:57], v[0:15]
	ds_read_b64_tr_b16 v[40:41], v47 offset:20224
	ds_read_b64_tr_b16 v[42:43], v47 offset:21376
	ds_read_b64_tr_b16 v[44:45], v47 offset:20288
	ds_read_b64_tr_b16 v[46:47], v47 offset:21440
	v_cvt_pk_bf16_f32 v36, v35, v36
	v_add_f32_e32 v33, v62, v63
	v_fmac_f32_e32 v33, v115, v34
	v_mov_b32_e32 v115, v33
	s_waitcnt lgkmcnt(4)
	v_mfma_f32_32x32x16_bf16 v[16:31], v[108:111], v[54:57], v[16:31]
	v_mov_b32_e32 v108, v124
	s_waitcnt lgkmcnt(2)
	v_mfma_f32_32x32x16_bf16 v[0:15], v[40:43], v[36:39], v[0:15]
	s_waitcnt lgkmcnt(0)
	v_mfma_f32_32x32x16_bf16 v[16:31], v[44:47], v[36:39], v[16:31]
